# k/v window output copies moved from MIX1 into the PAPR tail (run by the 224 workgroups without a second GEMM round)
# baseline (speedup 1.0000x reference)
.LBB0_15:
	s_load_dwordx16 s[16:31], s[0:1], 0x0
	s_load_dwordx16 s[36:51], s[0:1], 0x40
	v_cmp_eq_u32_e64 s[2:3], 0, v128
	s_waitcnt lgkmcnt(0)
	v_writelane_b32 v235, s20, 44
	v_writelane_b32 v235, s21, 45
	v_writelane_b32 v235, s22, 46
	v_writelane_b32 v235, s23, 47
	v_writelane_b32 v235, s36, 1
	s_nop 1
	v_writelane_b32 v235, s37, 2
	v_writelane_b32 v235, s38, 3
	v_writelane_b32 v235, s39, 4
	v_writelane_b32 v235, s40, 5
	v_writelane_b32 v235, s41, 6
	v_writelane_b32 v235, s42, 7
	v_writelane_b32 v235, s43, 8
	v_writelane_b32 v235, s44, 9
	v_writelane_b32 v235, s45, 10
	v_writelane_b32 v235, s46, 11
	v_writelane_b32 v235, s47, 12
	v_writelane_b32 v235, s48, 13
	v_writelane_b32 v235, s49, 14
	v_writelane_b32 v235, s50, 15
	v_writelane_b32 v235, s51, 16
	s_load_dwordx16 s[36:51], s[0:1], 0x80
	s_mov_b64 s[0:1], exec
	v_writelane_b32 v235, s2, 17
	s_nop 1
	v_writelane_b32 v235, s3, 18
	s_and_b64 s[2:3], s[0:1], s[2:3]
	s_mov_b64 exec, s[2:3]
	s_cbranch_execz .LBB0_17
	s_add_i32 s2, 0, 0x23ff0
	v_mov_b32_e32 v0, 0
	v_mov_b32_e32 v1, s2
	s_add_i32 s2, 0, 0x23ff4
	ds_write_b32 v1, v0
	v_mov_b32_e32 v1, s2
	ds_write_b32 v1, v0

.LBB0_1031:
.LBB0_1097:
.LBB0_1098:
	s_cmp_lt_i32 s92, 9
	s_cselect_b64 s[2:3], -1, 0
	s_cmp_gt_i32 s93, 8
	s_cselect_b64 s[4:5], -1, 0
	s_and_b64 s[4:5], s[2:3], s[4:5]
	s_andn2_b64 vcc, exec, s[4:5]
	s_cbranch_vccnz .LBB0_1157
	s_andn2_b64 vcc, exec, s[0:1]
	s_cbranch_vccnz .LBB0_1153
	s_waitcnt vmcnt(0)
	s_waitcnt vmcnt(0)
	s_barrier
	s_mov_b64 s[0:1], exec
	v_readlane_b32 s4, v235, 17
	v_readlane_b32 s5, v235, 18
	s_and_b64 s[4:5], s[0:1], s[4:5]
	s_mov_b64 exec, s[4:5]
	s_cbranch_execz .LBB0_1152
	s_add_i32 s4, 0, 0x23ff0
	v_mov_b32_e32 v0, s4
	s_waitcnt vmcnt(0) expcnt(0) lgkmcnt(0)
	ds_read_b32 v2, v0
	s_add_i32 s4, 0, 0x23ff4
	v_mov_b32_e32 v0, s4
	ds_read_b32 v0, v0
	s_waitcnt lgkmcnt(1)
	v_cmp_ne_u32_e32 vcc, 0, v2
	s_cbranch_vccnz .LBB0_1116
	v_readlane_b32 s4, v235, 0
	s_mul_i32 s18, s95, s4
	s_add_u32 s4, s50, 0x1000
	s_addc_u32 s5, s51, 0
	s_add_u32 s6, s50, 0x1100
	s_addc_u32 s7, s51, 0
	s_add_u32 s8, s50, 0x1200
	s_addc_u32 s9, s51, 0
	s_add_u32 s10, s50, 0x1300
	s_mul_i32 s18, s18, s94
	s_addc_u32 s11, s51, 0
	s_mov_b32 s19, 1
	v_mov_b32_e32 v16, 0
	s_branch .LBB0_1104

.Lcopy_entry:
	v_readlane_b32 s84, v235, 44
	v_readlane_b32 s85, v235, 45
	v_readlane_b32 s86, v235, 46
	v_readlane_b32 s87, v235, 47
	s_mov_b32 s88, 0
	s_cmp_lg_u32 s94, 0x100
	s_cbranch_scc1 .Lcopy_go
	s_cmp_lt_u32 s34, 32
	s_cbranch_scc1 .Lcopy_skip
	s_sub_u32 s34, s34, 32
	s_movk_i32 s94, 0xe0
	s_mov_b32 s88, 1
.Lcopy_go:
	s_nop 4
	s_add_u32 s2, s50, 0x14705000
	v_lshl_add_u32 v99, s34, 9, v128
	s_mov_b32 s4, 0x8000
	s_addc_u32 s3, s51, 0
	s_lshl_b32 s78, s94, 9
	v_cmp_gt_i32_e32 vcc, s4, v99
	s_and_saveexec_b64 s[6:7], vcc
	s_cbranch_execz .LBB0_1034
	v_lshlrev_b32_e32 v60, 2, v128
	s_waitcnt vmcnt(0)
	v_lshl_add_u32 v62, s34, 11, v60
	s_lshl_b32 s10, s94, 11
	s_mov_b64 s[8:9], 0
	s_movk_i32 s11, 0x1000
	v_mov_b32_e32 v61, 0
	s_movk_i32 s68, 0x4000
	v_mov_b32_e32 v63, 0xa00
	v_mov_b32_e32 v64, 0x800
	s_mov_b32 s69, 0x5920000
	v_mov_b32_e32 v65, 0x4840000
	v_mov_b32_e32 v66, 0x4800000
	s_movk_i32 s70, 0x7fff
	v_mov_b32_e32 v67, v99
.LBB0_1033:
	v_bfe_u32 v60, v67, 6, 7
	v_lshrrev_b32_e32 v68, 1, v67
	v_and_or_b32 v60, v68, s11, v60
	v_mul_u32_u24_e32 v60, 0x2e00, v60
	v_cmp_gt_u32_e32 vcc, s68, v67
	v_lshlrev_b32_e32 v60, 1, v60
	v_and_b32_e32 v72, 0xfc, v62
	v_lshl_add_u64 v[68:69], s[2:3], 0, v[60:61]
	v_cndmask_b32_e32 v60, v63, v64, vcc
	v_lshl_add_u64 v[68:69], v[68:69], 0, v[60:61]
	v_lshlrev_b32_e32 v60, 1, v72
	v_lshl_add_u64 v[68:69], v[68:69], 0, v[60:61]
	v_add_co_u32_e64 v68, s[4:5], s69, v68
	v_lshlrev_b32_e32 v73, 4, v67
	s_nop 0
	v_addc_co_u32_e64 v69, s[4:5], 0, v69, s[4:5]
	global_load_dwordx2 v[70:71], v[68:69], off
	v_cndmask_b32_e32 v60, v65, v66, vcc
	v_add_u32_e32 v67, s78, v67
	v_lshl_add_u64 v[68:69], s[48:49], 0, v[60:61]
	v_and_b32_e32 v60, 0x3fc00, v73
	v_cmp_lt_i32_e64 s[4:5], s70, v67
	v_lshl_add_u64 v[68:69], v[68:69], 0, v[60:61]
	v_lshlrev_b32_e32 v60, 2, v72
	v_add_u32_e32 v62, s10, v62
	s_or_b64 s[8:9], s[4:5], s[8:9]
	v_lshl_add_u64 v[72:73], v[68:69], 0, v[60:61]
	s_waitcnt vmcnt(0)
	v_lshlrev_b32_e32 v68, 16, v70
	v_and_b32_e32 v69, 0xffff0000, v70
	v_lshlrev_b32_e32 v70, 16, v71
	v_and_b32_e32 v71, 0xffff0000, v71
	global_store_dwordx4 v[72:73], v[68:71], off
	s_andn2_b64 exec, exec, s[8:9]
	s_cbranch_execnz .LBB0_1033
.LBB0_1034:
	s_or_b64 exec, exec, s[6:7]
	s_mov_b32 s79, 0x200000
	v_cmp_gt_i32_e32 vcc, s79, v99
	s_and_saveexec_b64 s[74:75], vcc
	s_cbranch_execz .Lcopy_done
	s_add_i32 s67, s78, s78
	s_add_i32 s4, s67, s78
	v_lshlrev_b32_e32 v60, 2, v128
	v_mov_b32_e32 v93, 0
	s_add_i32 s4, s67, s4
	s_lshl_b32 s33, s94, 10
	s_lshl_b32 s35, s94, 12
	v_lshl_add_u32 v94, s34, 11, v60
	s_lshl_b32 s52, s94, 14
	s_mul_i32 s53, s94, 0x600
	s_mul_i32 s54, s94, 0x1800
	s_lshl_b32 s55, s94, 11
	s_lshl_b32 s56, s94, 13
	s_mul_i32 s57, s94, 0xa00
	s_mul_i32 s58, s94, 0x2800
	s_mul_i32 s59, s94, 0xc00
	s_mul_i32 s80, s94, 0x3000
	s_mul_i32 s81, s94, 0xe00
	s_mul_i32 s82, s94, 0x3800
	s_mov_b64 s[24:25], 0
	s_movk_i32 s83, 0x77
	s_movk_i32 s64, 0x1f88
	s_mov_b32 s65, 0x100000
	s_mov_b32 s66, 0x1fffff
	v_mov_b32_e32 v95, 0xa00
	v_mov_b32_e32 v96, 0x800
	v_mov_b32_e32 v97, 0x5a80000
	v_mov_b32_e32 v98, 0x4a80000
	s_add_i32 s67, s67, s4
	v_mov_b32_e32 v60, v93
	v_mov_b32_e32 v61, v93
	s_waitcnt vmcnt(0)
	v_mov_b32_e32 v62, v93
	v_mov_b32_e32 v63, v93
	v_mov_b32_e32 v64, v93
	v_mov_b32_e32 v65, v93
	v_mov_b32_e32 v66, v93
	v_mov_b32_e32 v67, v93
	v_mov_b32_e32 v68, v93
	v_mov_b32_e32 v69, v93
	v_mov_b32_e32 v70, v93
	v_mov_b32_e32 v71, v93
	v_mov_b32_e32 v72, v93
	v_mov_b32_e32 v73, v93
	v_mov_b32_e32 v74, v93
	v_mov_b32_e32 v75, v93
	v_mov_b32_e32 v76, v93
	v_mov_b32_e32 v77, v93
	v_mov_b32_e32 v78, v93
	v_mov_b32_e32 v79, v93
	v_mov_b32_e32 v80, v93
	v_mov_b32_e32 v81, v93
	v_mov_b32_e32 v82, v93
	v_mov_b32_e32 v83, v93
	v_mov_b32_e32 v84, v93
	v_mov_b32_e32 v85, v93
	v_mov_b32_e32 v86, v93
	v_mov_b32_e32 v87, v93
	s_branch .LBB0_1037
.LBB0_1036:
	s_or_b64 exec, exec, s[4:5]
	v_add_u32_e32 v99, s67, v100
	v_cmp_lt_i32_e32 vcc, s66, v99
	s_or_b64 s[24:25], vcc, s[24:25]
	v_add_u32_e32 v94, s52, v94
	s_andn2_b64 exec, exec, s[24:25]
	s_cbranch_execz .Lcopy_done
.LBB0_1037:
	v_bfe_u32 v100, v99, 6, 7
	v_and_b32_e32 v101, 0xfc, v94
	v_bfe_u32 v102, v99, 13, 7
	v_cmp_lt_u32_e32 vcc, s83, v100
	s_and_saveexec_b64 s[4:5], vcc
	s_xor_b64 s[4:5], exec, s[4:5]
	s_cbranch_execz .LBB0_1039
	v_lshlrev_b32_e32 v88, 3, v102
	v_add3_u32 v88, v100, v88, s64
	v_mul_u32_u24_e32 v92, 0x5c00, v88
	v_cmp_gt_u32_e32 vcc, s65, v99
	v_lshl_add_u64 v[88:89], s[2:3], 0, v[92:93]
	s_nop 0
	v_cndmask_b32_e32 v92, v95, v96, vcc
	v_lshl_add_u64 v[88:89], v[88:89], 0, v[92:93]
	v_lshlrev_b32_e32 v92, 1, v101
	v_lshl_add_u64 v[88:89], v[88:89], 0, v[92:93]
	global_load_dwordx2 v[90:91], v[88:89], off
	s_waitcnt vmcnt(0)
	v_lshlrev_b32_e32 v88, 16, v90
	v_and_b32_e32 v89, 0xffff0000, v90
	v_lshlrev_b32_e32 v90, 16, v91
	v_and_b32_e32 v91, 0xffff0000, v91
.LBB0_1039:
	s_or_saveexec_b64 s[4:5], s[4:5]
	v_lshlrev_b32_e32 v92, 2, v101
	s_xor_b64 exec, exec, s[4:5]
	s_cbranch_execz .LBB0_1041
	v_mov_b32_e32 v88, s87
	v_mov_b32_e32 v89, s85
	v_cmp_gt_u32_e32 vcc, s65, v99
	v_mov_b32_e32 v90, s84
	v_mov_b32_e32 v91, v93
	v_cndmask_b32_e32 v89, v88, v89, vcc
	v_mov_b32_e32 v88, s86
	v_cndmask_b32_e32 v88, v88, v90, vcc
	v_lshlrev_b32_e32 v90, 10, v100
	v_lshl_or_b32 v90, v102, 17, v90
	v_lshl_add_u64 v[88:89], v[88:89], 0, v[90:91]
	v_lshl_add_u64 v[88:89], v[88:89], 0, v[92:93]
	v_add_co_u32_e32 v88, vcc, 0x2000, v88
	s_nop 1
	v_addc_co_u32_e32 v89, vcc, 0, v89, vcc
	global_load_dwordx4 v[88:91], v[88:89], off
.LBB0_1041:
	s_or_b64 exec, exec, s[4:5]
	v_add_u32_e32 v100, s78, v99
	v_cmp_gt_i32_e64 s[4:5], s79, v100
	s_and_saveexec_b64 s[6:7], s[4:5]
	s_cbranch_execz .LBB0_1047
	v_bfe_u32 v102, v100, 6, 7
	v_bfe_u32 v103, v100, 13, 7
	v_cmp_lt_u32_e32 vcc, s83, v102
	s_and_saveexec_b64 s[8:9], vcc
	s_xor_b64 s[8:9], exec, s[8:9]
	s_cbranch_execz .LBB0_1044
	v_lshlrev_b32_e32 v60, 3, v103
	v_add3_u32 v60, v102, v60, s64
	v_mul_u32_u24_e32 v60, 0x5c00, v60
	v_mov_b32_e32 v61, v93
	v_cmp_gt_u32_e32 vcc, s65, v100
	v_lshl_add_u64 v[60:61], s[2:3], 0, v[60:61]
	v_mov_b32_e32 v63, v93
	v_cndmask_b32_e32 v62, v95, v96, vcc
	v_lshl_add_u64 v[60:61], v[60:61], 0, v[62:63]
	v_lshlrev_b32_e32 v62, 1, v101
	v_lshl_add_u64 v[60:61], v[60:61], 0, v[62:63]
	global_load_dwordx2 v[62:63], v[60:61], off
	s_waitcnt vmcnt(0)
	v_lshlrev_b32_e32 v60, 16, v62
	v_and_b32_e32 v61, 0xffff0000, v62
	v_lshlrev_b32_e32 v62, 16, v63
	v_and_b32_e32 v63, 0xffff0000, v63
.LBB0_1044:
	s_andn2_saveexec_b64 s[8:9], s[8:9]
	s_cbranch_execz .LBB0_1046
	v_mov_b32_e32 v60, s87
	v_mov_b32_e32 v61, s85
	v_cmp_gt_u32_e32 vcc, s65, v100
	v_mov_b32_e32 v62, s84
	v_mov_b32_e32 v63, v93
	v_cndmask_b32_e32 v61, v60, v61, vcc
	v_mov_b32_e32 v60, s86
	v_cndmask_b32_e32 v60, v60, v62, vcc
	v_lshlrev_b32_e32 v62, 10, v102
	v_lshl_or_b32 v62, v103, 17, v62
	v_lshl_add_u64 v[60:61], v[60:61], 0, v[62:63]
	v_lshl_add_u64 v[60:61], v[60:61], 0, v[92:93]
	v_add_co_u32_e32 v60, vcc, 0x2000, v60
	s_nop 1
	v_addc_co_u32_e32 v61, vcc, 0, v61, vcc
	global_load_dwordx4 v[60:63], v[60:61], off

.LBB0_1047:
	s_or_b64 exec, exec, s[6:7]
	v_add_u32_e32 v102, s33, v99
	v_cmp_gt_i32_e64 s[6:7], s79, v102
	s_and_saveexec_b64 s[8:9], s[6:7]
	s_cbranch_execz .LBB0_1053
	v_bfe_u32 v103, v102, 6, 7
	v_bfe_u32 v104, v102, 13, 7
	v_cmp_lt_u32_e32 vcc, s83, v103
	s_and_saveexec_b64 s[10:11], vcc
	s_xor_b64 s[10:11], exec, s[10:11]
	s_cbranch_execz .LBB0_1050
	v_lshlrev_b32_e32 v64, 3, v104
	v_add3_u32 v64, v103, v64, s64
	v_mul_u32_u24_e32 v64, 0x5c00, v64
	v_mov_b32_e32 v65, v93
	v_cmp_gt_u32_e32 vcc, s65, v102
	v_lshl_add_u64 v[64:65], s[2:3], 0, v[64:65]
	v_mov_b32_e32 v67, v93
	v_cndmask_b32_e32 v66, v95, v96, vcc
	v_lshl_add_u64 v[64:65], v[64:65], 0, v[66:67]
	v_lshlrev_b32_e32 v66, 1, v101
	v_lshl_add_u64 v[64:65], v[64:65], 0, v[66:67]
	global_load_dwordx2 v[66:67], v[64:65], off
	s_waitcnt vmcnt(0)
	v_lshlrev_b32_e32 v64, 16, v66
	v_and_b32_e32 v65, 0xffff0000, v66
	v_lshlrev_b32_e32 v66, 16, v67
	v_and_b32_e32 v67, 0xffff0000, v67
.LBB0_1050:
	s_andn2_saveexec_b64 s[10:11], s[10:11]
	s_cbranch_execz .LBB0_1052
	v_mov_b32_e32 v64, s87
	v_mov_b32_e32 v65, s85
	v_cmp_gt_u32_e32 vcc, s65, v102
	v_mov_b32_e32 v66, s84
	v_mov_b32_e32 v67, v93
	v_cndmask_b32_e32 v65, v64, v65, vcc
	v_mov_b32_e32 v64, s86
	v_cndmask_b32_e32 v64, v64, v66, vcc
	v_lshlrev_b32_e32 v66, 10, v103
	v_lshl_or_b32 v66, v104, 17, v66
	v_lshl_add_u64 v[64:65], v[64:65], 0, v[66:67]
	v_lshl_add_u64 v[64:65], v[64:65], 0, v[92:93]
	v_add_co_u32_e32 v64, vcc, 0x2000, v64
	s_nop 1
	v_addc_co_u32_e32 v65, vcc, 0, v65, vcc
	global_load_dwordx4 v[64:67], v[64:65], off

.LBB0_1053:
	s_or_b64 exec, exec, s[8:9]
	v_add_u32_e32 v103, s53, v99
	v_cmp_gt_i32_e64 s[8:9], s79, v103
	s_and_saveexec_b64 s[10:11], s[8:9]
	s_cbranch_execz .LBB0_1059
	v_bfe_u32 v104, v103, 6, 7
	v_bfe_u32 v105, v103, 13, 7
	v_cmp_lt_u32_e32 vcc, s83, v104
	s_and_saveexec_b64 s[68:69], vcc
	s_xor_b64 s[68:69], exec, s[68:69]
	s_cbranch_execz .LBB0_1056
	v_lshlrev_b32_e32 v68, 3, v105
	v_add3_u32 v68, v104, v68, s64
	v_mul_u32_u24_e32 v68, 0x5c00, v68
	v_mov_b32_e32 v69, v93
	v_cmp_gt_u32_e32 vcc, s65, v103
	v_lshl_add_u64 v[68:69], s[2:3], 0, v[68:69]
	v_mov_b32_e32 v71, v93
	v_cndmask_b32_e32 v70, v95, v96, vcc
	v_lshl_add_u64 v[68:69], v[68:69], 0, v[70:71]
	v_lshlrev_b32_e32 v70, 1, v101
	v_lshl_add_u64 v[68:69], v[68:69], 0, v[70:71]
	global_load_dwordx2 v[70:71], v[68:69], off
	s_waitcnt vmcnt(0)
	v_lshlrev_b32_e32 v68, 16, v70
	v_and_b32_e32 v69, 0xffff0000, v70
	v_lshlrev_b32_e32 v70, 16, v71
	v_and_b32_e32 v71, 0xffff0000, v71
.LBB0_1056:
	s_andn2_saveexec_b64 s[68:69], s[68:69]
	s_cbranch_execz .LBB0_1058
	v_mov_b32_e32 v68, s87
	v_mov_b32_e32 v69, s85
	v_cmp_gt_u32_e32 vcc, s65, v103
	v_mov_b32_e32 v70, s84
	v_mov_b32_e32 v71, v93
	v_cndmask_b32_e32 v69, v68, v69, vcc
	v_mov_b32_e32 v68, s86
	v_cndmask_b32_e32 v68, v68, v70, vcc
	v_lshlrev_b32_e32 v70, 10, v104
	v_lshl_or_b32 v70, v105, 17, v70
	v_lshl_add_u64 v[68:69], v[68:69], 0, v[70:71]
	v_lshl_add_u64 v[68:69], v[68:69], 0, v[92:93]
	v_add_co_u32_e32 v68, vcc, 0x2000, v68
	s_nop 1
	v_addc_co_u32_e32 v69, vcc, 0, v69, vcc
	global_load_dwordx4 v[68:71], v[68:69], off
.LBB0_1058:
	s_or_b64 exec, exec, s[68:69]
.LBB0_1059:
	s_or_b64 exec, exec, s[10:11]
	v_add_u32_e32 v104, s55, v99
	v_cmp_gt_i32_e64 s[10:11], s79, v104
	s_and_saveexec_b64 s[68:69], s[10:11]
	s_cbranch_execz .LBB0_1065
	v_bfe_u32 v105, v104, 6, 7
	v_bfe_u32 v106, v104, 13, 7
	v_cmp_lt_u32_e32 vcc, s83, v105
	s_and_saveexec_b64 s[70:71], vcc
	s_xor_b64 s[70:71], exec, s[70:71]
	s_cbranch_execz .LBB0_1062
	v_lshlrev_b32_e32 v72, 3, v106
	v_add3_u32 v72, v105, v72, s64
	v_mul_u32_u24_e32 v72, 0x5c00, v72
	v_mov_b32_e32 v73, v93
	v_cmp_gt_u32_e32 vcc, s65, v104
	v_lshl_add_u64 v[72:73], s[2:3], 0, v[72:73]
	v_mov_b32_e32 v75, v93
	v_cndmask_b32_e32 v74, v95, v96, vcc
	v_lshl_add_u64 v[72:73], v[72:73], 0, v[74:75]
	v_lshlrev_b32_e32 v74, 1, v101
	v_lshl_add_u64 v[72:73], v[72:73], 0, v[74:75]
	global_load_dwordx2 v[74:75], v[72:73], off
	s_waitcnt vmcnt(0)
	v_lshlrev_b32_e32 v72, 16, v74
	v_and_b32_e32 v73, 0xffff0000, v74
	v_lshlrev_b32_e32 v74, 16, v75
	v_and_b32_e32 v75, 0xffff0000, v75
.LBB0_1062:
	s_andn2_saveexec_b64 s[70:71], s[70:71]
	s_cbranch_execz .LBB0_1064
	v_mov_b32_e32 v72, s87
	v_mov_b32_e32 v73, s85
	v_cmp_gt_u32_e32 vcc, s65, v104
	v_mov_b32_e32 v74, s84
	v_mov_b32_e32 v75, v93
	v_cndmask_b32_e32 v73, v72, v73, vcc
	v_mov_b32_e32 v72, s86
	v_cndmask_b32_e32 v72, v72, v74, vcc
	v_lshlrev_b32_e32 v74, 10, v105
	v_lshl_or_b32 v74, v106, 17, v74
	v_lshl_add_u64 v[72:73], v[72:73], 0, v[74:75]
	v_lshl_add_u64 v[72:73], v[72:73], 0, v[92:93]
	v_add_co_u32_e32 v72, vcc, 0x2000, v72
	s_nop 1
	v_addc_co_u32_e32 v73, vcc, 0, v73, vcc
	global_load_dwordx4 v[72:75], v[72:73], off
.LBB0_1064:
	s_or_b64 exec, exec, s[70:71]
.LBB0_1065:
	s_or_b64 exec, exec, s[68:69]
	v_add_u32_e32 v105, s57, v99
	v_cmp_gt_i32_e64 s[68:69], s79, v105
	s_and_saveexec_b64 s[70:71], s[68:69]
	s_cbranch_execz .LBB0_1071
	v_bfe_u32 v106, v105, 6, 7
	v_bfe_u32 v107, v105, 13, 7
	v_cmp_lt_u32_e32 vcc, s83, v106
	s_and_saveexec_b64 s[72:73], vcc
	s_xor_b64 s[72:73], exec, s[72:73]
	s_cbranch_execz .LBB0_1068
	v_lshlrev_b32_e32 v76, 3, v107
	v_add3_u32 v76, v106, v76, s64
	v_mul_u32_u24_e32 v76, 0x5c00, v76
	v_mov_b32_e32 v77, v93
	v_cmp_gt_u32_e32 vcc, s65, v105
	v_lshl_add_u64 v[76:77], s[2:3], 0, v[76:77]
	v_mov_b32_e32 v79, v93
	v_cndmask_b32_e32 v78, v95, v96, vcc
	v_lshl_add_u64 v[76:77], v[76:77], 0, v[78:79]
	v_lshlrev_b32_e32 v78, 1, v101
	v_lshl_add_u64 v[76:77], v[76:77], 0, v[78:79]
	global_load_dwordx2 v[78:79], v[76:77], off
	s_waitcnt vmcnt(0)
	v_lshlrev_b32_e32 v76, 16, v78
	v_and_b32_e32 v77, 0xffff0000, v78
	v_lshlrev_b32_e32 v78, 16, v79
	v_and_b32_e32 v79, 0xffff0000, v79
.LBB0_1068:
	s_andn2_saveexec_b64 s[72:73], s[72:73]
	s_cbranch_execz .LBB0_1070
	v_mov_b32_e32 v76, s87
	v_mov_b32_e32 v77, s85
	v_cmp_gt_u32_e32 vcc, s65, v105
	v_mov_b32_e32 v78, s84
	v_mov_b32_e32 v79, v93
	v_cndmask_b32_e32 v77, v76, v77, vcc
	v_mov_b32_e32 v76, s86
	v_cndmask_b32_e32 v76, v76, v78, vcc
	v_lshlrev_b32_e32 v78, 10, v106
	v_lshl_or_b32 v78, v107, 17, v78
	v_lshl_add_u64 v[76:77], v[76:77], 0, v[78:79]
	v_lshl_add_u64 v[76:77], v[76:77], 0, v[92:93]
	v_add_co_u32_e32 v76, vcc, 0x2000, v76
	s_nop 1
	v_addc_co_u32_e32 v77, vcc, 0, v77, vcc
	global_load_dwordx4 v[76:79], v[76:77], off
.LBB0_1070:
	s_or_b64 exec, exec, s[72:73]
.LBB0_1071:
	s_or_b64 exec, exec, s[70:71]
	v_add_u32_e32 v106, s59, v99
	v_cmp_gt_i32_e64 s[70:71], s79, v106
	s_and_saveexec_b64 s[72:73], s[70:71]
	s_cbranch_execz .LBB0_1077
	v_bfe_u32 v107, v106, 6, 7
	v_bfe_u32 v108, v106, 13, 7
	v_cmp_lt_u32_e32 vcc, s83, v107
	s_and_saveexec_b64 s[26:27], vcc
	s_xor_b64 s[26:27], exec, s[26:27]
	s_cbranch_execz .LBB0_1074
	v_lshlrev_b32_e32 v80, 3, v108
	v_add3_u32 v80, v107, v80, s64
	v_mul_u32_u24_e32 v80, 0x5c00, v80
	v_mov_b32_e32 v81, v93
	v_cmp_gt_u32_e32 vcc, s65, v106
	v_lshl_add_u64 v[80:81], s[2:3], 0, v[80:81]
	v_mov_b32_e32 v83, v93
	v_cndmask_b32_e32 v82, v95, v96, vcc
	v_lshl_add_u64 v[80:81], v[80:81], 0, v[82:83]
	v_lshlrev_b32_e32 v82, 1, v101
	v_lshl_add_u64 v[80:81], v[80:81], 0, v[82:83]
	global_load_dwordx2 v[82:83], v[80:81], off
	s_waitcnt vmcnt(0)
	v_lshlrev_b32_e32 v80, 16, v82
	v_and_b32_e32 v81, 0xffff0000, v82
	v_lshlrev_b32_e32 v82, 16, v83
	v_and_b32_e32 v83, 0xffff0000, v83
.LBB0_1074:
	s_andn2_saveexec_b64 s[26:27], s[26:27]
	s_cbranch_execz .LBB0_1076
	v_mov_b32_e32 v80, s87
	v_mov_b32_e32 v81, s85
	v_cmp_gt_u32_e32 vcc, s65, v106
	v_mov_b32_e32 v82, s84
	v_mov_b32_e32 v83, v93
	v_cndmask_b32_e32 v81, v80, v81, vcc
	v_mov_b32_e32 v80, s86
	v_cndmask_b32_e32 v80, v80, v82, vcc
	v_lshlrev_b32_e32 v82, 10, v107
	v_lshl_or_b32 v82, v108, 17, v82
	v_lshl_add_u64 v[80:81], v[80:81], 0, v[82:83]
	v_lshl_add_u64 v[80:81], v[80:81], 0, v[92:93]
	v_add_co_u32_e32 v80, vcc, 0x2000, v80
	s_nop 1
	v_addc_co_u32_e32 v81, vcc, 0, v81, vcc
	global_load_dwordx4 v[80:83], v[80:81], off

.LBB0_1077:
	s_or_b64 exec, exec, s[72:73]
	v_add_u32_e32 v107, s81, v99
	v_cmp_gt_i32_e64 s[72:73], s79, v107
	s_and_saveexec_b64 s[26:27], s[72:73]
	s_cbranch_execz .LBB0_1083
	v_bfe_u32 v108, v107, 6, 7
	v_bfe_u32 v109, v107, 13, 7
	v_cmp_lt_u32_e32 vcc, s83, v108
	s_and_saveexec_b64 s[76:77], vcc
	s_xor_b64 s[76:77], exec, s[76:77]
	s_cbranch_execz .LBB0_1080
	v_lshlrev_b32_e32 v84, 3, v109
	v_add3_u32 v84, v108, v84, s64
	v_mul_u32_u24_e32 v84, 0x5c00, v84
	v_mov_b32_e32 v85, v93
	v_cmp_gt_u32_e32 vcc, s65, v107
	v_lshl_add_u64 v[84:85], s[2:3], 0, v[84:85]
	v_mov_b32_e32 v87, v93
	v_cndmask_b32_e32 v86, v95, v96, vcc
	v_lshl_add_u64 v[84:85], v[84:85], 0, v[86:87]
	v_lshlrev_b32_e32 v86, 1, v101
	v_lshl_add_u64 v[84:85], v[84:85], 0, v[86:87]
	global_load_dwordx2 v[86:87], v[84:85], off
	s_waitcnt vmcnt(0)
	v_lshlrev_b32_e32 v84, 16, v86
	v_and_b32_e32 v85, 0xffff0000, v86
	v_lshlrev_b32_e32 v86, 16, v87
	v_and_b32_e32 v87, 0xffff0000, v87
.LBB0_1080:
	s_andn2_saveexec_b64 s[76:77], s[76:77]
	s_cbranch_execz .LBB0_1082
	v_mov_b32_e32 v84, s87
	v_mov_b32_e32 v85, s85
	v_cmp_gt_u32_e32 vcc, s65, v107
	v_mov_b32_e32 v86, s84
	v_mov_b32_e32 v87, v93
	v_cndmask_b32_e32 v85, v84, v85, vcc
	v_mov_b32_e32 v84, s86
	v_cndmask_b32_e32 v84, v84, v86, vcc
	v_lshlrev_b32_e32 v86, 10, v108
	v_lshl_or_b32 v86, v109, 17, v86
	v_lshl_add_u64 v[84:85], v[84:85], 0, v[86:87]
	v_lshl_add_u64 v[84:85], v[84:85], 0, v[92:93]
	v_add_co_u32_e32 v84, vcc, 0x2000, v84
	s_nop 1
	v_addc_co_u32_e32 v85, vcc, 0, v85, vcc
	global_load_dwordx4 v[84:87], v[84:85], off
.LBB0_1082:
	s_or_b64 exec, exec, s[76:77]
.LBB0_1083:
	s_or_b64 exec, exec, s[26:27]
	v_cmp_gt_u32_e32 vcc, s65, v99
	v_mov_b32_e32 v109, v93
	v_and_b32_e32 v99, 0x3fff00, v94
	v_cndmask_b32_e32 v108, v97, v98, vcc
	v_lshl_add_u64 v[108:109], s[48:49], 0, v[108:109]
	v_lshlrev_b32_e32 v110, 2, v99
	v_mov_b32_e32 v111, v93
	v_lshl_add_u64 v[108:109], v[108:109], 0, v[110:111]
	v_lshl_add_u64 v[108:109], v[108:109], 0, v[92:93]
	s_waitcnt vmcnt(0)
	global_store_dwordx4 v[108:109], v[88:91], off
	s_and_saveexec_b64 s[26:27], s[4:5]
	s_cbranch_execnz .LBB0_1090
	s_or_b64 exec, exec, s[26:27]
	s_and_saveexec_b64 s[4:5], s[6:7]
	s_cbranch_execnz .LBB0_1091

.LBB0_1087:
	s_or_b64 exec, exec, s[4:5]
	s_and_saveexec_b64 s[4:5], s[68:69]
	s_cbranch_execnz .LBB0_1094
.LBB0_1088:
	s_or_b64 exec, exec, s[4:5]
	s_and_saveexec_b64 s[4:5], s[70:71]
	s_cbranch_execnz .LBB0_1095
.LBB0_1089:
	s_or_b64 exec, exec, s[4:5]
	s_and_saveexec_b64 s[4:5], s[72:73]
	s_cbranch_execz .LBB0_1036
	s_branch .LBB0_1096
.LBB0_1090:
	v_cmp_gt_u32_e32 vcc, s65, v100
	v_add_u32_e32 v90, s55, v94
	v_mov_b32_e32 v89, v93
	v_cndmask_b32_e32 v88, v97, v98, vcc
	v_and_b32_e32 v90, 0x3fff00, v90
	v_lshl_add_u64 v[88:89], s[48:49], 0, v[88:89]
	v_lshlrev_b32_e32 v90, 2, v90
	v_mov_b32_e32 v91, v93
	v_lshl_add_u64 v[88:89], v[88:89], 0, v[90:91]
	v_lshl_add_u64 v[88:89], v[88:89], 0, v[92:93]
	global_store_dwordx4 v[88:89], v[60:63], off
	s_or_b64 exec, exec, s[26:27]
	s_and_saveexec_b64 s[4:5], s[6:7]
	s_cbranch_execz .LBB0_1085
.LBB0_1091:
	v_cmp_gt_u32_e32 vcc, s65, v102
	v_add_u32_e32 v90, s35, v94
	v_mov_b32_e32 v89, v93
	v_cndmask_b32_e32 v88, v97, v98, vcc
	v_and_b32_e32 v90, 0x3fff00, v90
	v_lshl_add_u64 v[88:89], s[48:49], 0, v[88:89]
	v_lshlrev_b32_e32 v90, 2, v90
	v_mov_b32_e32 v91, v93
	v_lshl_add_u64 v[88:89], v[88:89], 0, v[90:91]
	v_lshl_add_u64 v[88:89], v[88:89], 0, v[92:93]
	global_store_dwordx4 v[88:89], v[64:67], off
	s_or_b64 exec, exec, s[4:5]
	s_and_saveexec_b64 s[4:5], s[8:9]
	s_cbranch_execz .LBB0_1086
.LBB0_1092:
	v_cmp_gt_u32_e32 vcc, s65, v103
	v_add_u32_e32 v90, s54, v94
	v_mov_b32_e32 v89, v93
	v_cndmask_b32_e32 v88, v97, v98, vcc
	v_and_b32_e32 v90, 0x3fff00, v90
	v_lshl_add_u64 v[88:89], s[48:49], 0, v[88:89]
	v_lshlrev_b32_e32 v90, 2, v90
	v_mov_b32_e32 v91, v93
	v_lshl_add_u64 v[88:89], v[88:89], 0, v[90:91]
	v_lshl_add_u64 v[88:89], v[88:89], 0, v[92:93]
	global_store_dwordx4 v[88:89], v[68:71], off
	s_or_b64 exec, exec, s[4:5]
	s_and_saveexec_b64 s[4:5], s[10:11]
	s_cbranch_execz .LBB0_1087
.LBB0_1093:
	v_cmp_gt_u32_e32 vcc, s65, v104
	v_add_u32_e32 v90, s56, v94
	v_mov_b32_e32 v89, v93
	v_cndmask_b32_e32 v88, v97, v98, vcc
	v_and_b32_e32 v90, 0x3fff00, v90
	v_lshl_add_u64 v[88:89], s[48:49], 0, v[88:89]
	v_lshlrev_b32_e32 v90, 2, v90
	v_mov_b32_e32 v91, v93
	v_lshl_add_u64 v[88:89], v[88:89], 0, v[90:91]
	v_lshl_add_u64 v[88:89], v[88:89], 0, v[92:93]
	global_store_dwordx4 v[88:89], v[72:75], off
	s_or_b64 exec, exec, s[4:5]
	s_and_saveexec_b64 s[4:5], s[68:69]
	s_cbranch_execz .LBB0_1088
.LBB0_1094:
	v_cmp_gt_u32_e32 vcc, s65, v105
	v_add_u32_e32 v90, s58, v94
	v_mov_b32_e32 v89, v93
	v_cndmask_b32_e32 v88, v97, v98, vcc
	v_and_b32_e32 v90, 0x3fff00, v90
	v_lshl_add_u64 v[88:89], s[48:49], 0, v[88:89]
	v_lshlrev_b32_e32 v90, 2, v90
	v_mov_b32_e32 v91, v93
	v_lshl_add_u64 v[88:89], v[88:89], 0, v[90:91]
	v_lshl_add_u64 v[88:89], v[88:89], 0, v[92:93]
	global_store_dwordx4 v[88:89], v[76:79], off
	s_or_b64 exec, exec, s[4:5]
	s_and_saveexec_b64 s[4:5], s[70:71]
	s_cbranch_execz .LBB0_1089
.LBB0_1095:
	v_cmp_gt_u32_e32 vcc, s65, v106
	v_add_u32_e32 v90, s80, v94
	v_mov_b32_e32 v89, v93
	v_cndmask_b32_e32 v88, v97, v98, vcc
	v_and_b32_e32 v90, 0x3fff00, v90
	v_lshl_add_u64 v[88:89], s[48:49], 0, v[88:89]
	v_lshlrev_b32_e32 v90, 2, v90
	v_mov_b32_e32 v91, v93
	v_lshl_add_u64 v[88:89], v[88:89], 0, v[90:91]
	v_lshl_add_u64 v[88:89], v[88:89], 0, v[92:93]
	global_store_dwordx4 v[88:89], v[80:83], off
	s_or_b64 exec, exec, s[4:5]
	s_and_saveexec_b64 s[4:5], s[72:73]
	s_cbranch_execz .LBB0_1036
.LBB0_1096:
	v_cmp_gt_u32_e32 vcc, s65, v107
	v_add_u32_e32 v90, s82, v94
	v_mov_b32_e32 v89, v93
	v_cndmask_b32_e32 v88, v97, v98, vcc
	v_and_b32_e32 v90, 0x3fff00, v90
	v_lshl_add_u64 v[88:89], s[48:49], 0, v[88:89]
	v_lshlrev_b32_e32 v90, 2, v90
	v_mov_b32_e32 v91, v93
	v_lshl_add_u64 v[88:89], v[88:89], 0, v[90:91]
	v_lshl_add_u64 v[88:89], v[88:89], 0, v[92:93]
	global_store_dwordx4 v[88:89], v[84:87], off
	s_branch .LBB0_1036
.Lcopy_done:
	s_or_b64 exec, exec, s[74:75]
	s_cmp_eq_u32 s88, 0
	s_cbranch_scc1 .Lcopy_skip
	s_add_u32 s34, s34, 32
	s_movk_i32 s94, 0x100
